# HGRN compute section: LDS operand reads hoisted with fresh registers and counted waits (on v52)
# baseline (speedup 1.0000x reference)
; #define LAS __attribute__((address_space(3)))
; __device__ __forceinline__ bf16x8 pack8(const f32x4 a, const f32x4 b) { const u32x4 v = {pk2(a[0], a[1]), pk2(a[2], a[3]), pk2(b[0], b[1]), pk2(b[2], b[3])}; return __builtin_bit_cast(bf16x8, v); }
; __device__ __forceinline__ void hgrn_chunked_bh(const Ctx& F, int b, int h) {
;     ...
;         {
;             bf16x8 qf[4][2];
; #pragma unroll
;             for (int s = 0; s < 4; ++s)
; #pragma unroll
;                 for (int nt = 0; nt < 2; ++nt) qf[s][nt] = ld_frag2(Ls + H_QM + (c16 + 16 * nt) * HQP + (32 * s + 4 * g) * 2);
;             f32x4 at[2][2];
; #pragma unroll
;             for (int mt = 0; mt < 2; ++mt)
; #pragma unroll
;                 for (int nt = 0; nt < 2; ++nt) at[mt][nt] = (f32x4){0.f, 0.f, 0.f, 0.f};
; #pragma unroll
;             for (int s = 0; s < 4; ++s)
; #pragma unroll
;                 for (int mt = 0; mt < 2; ++mt) { const bf16x8 ka = ld_frag2(Ls + H_KM + (c16 + 16 * mt) * HQP + (32 * s + 4 * g) * 2);
; #pragma unroll
;                     for (int nt = 0; nt < 2; ++nt) at[mt][nt] = __builtin_amdgcn_mfma_f32_16x16x32_bf16(ka, qf[s][nt], at[mt][nt], 0, 0, 0); }
; #pragma unroll
;             for (int mt = 0; mt < 2; ++mt)
; #pragma unroll
;                 for (int nt = 0; nt < 2; ++nt)
; #pragma unroll
;                     for (int r = 0; r < 4; ++r) if (16 * mt + 4 * g + r > c16 + 16 * nt) at[mt][nt][r] = 0.f;
;             f32x4 oT[2] = {(f32x4){0.f, 0.f, 0.f, 0.f}, (f32x4){0.f, 0.f, 0.f, 0.f}};
; #pragma unroll
;             for (int s = 0; s < 4; ++s) {
;                 const f32x4 e0 = *(const LAS f32x4*)(Ls + H_EM + (32 * s + 4 * g) * 4), e1 = *(const LAS f32x4*)(Ls + H_EM + (32 * s + 16 + 4 * g) * 4);
;                 const bf16x8 sA = pack8(st[2 * s] * e0, st[2 * s + 1] * e1);
; #pragma unroll
;                 for (int nt = 0; nt < 2; ++nt) oT[nt] = __builtin_amdgcn_mfma_f32_16x16x32_bf16(sA, qf[s][nt], oT[nt], 0, 0, 0);
;             }
.Lhg_nopf:
	s_waitcnt lgkmcnt(0)
	s_barrier
	ds_read2_b64 v[192:195], v148 offset0:64 offset1:68
	ds_read2_b64 v[196:199], v152 offset1:4
	ds_read2_b64 v[200:203], v156 offset0:32 offset1:36
	v_add_u32_e32 v204, 0x3000, v152
	ds_read2_b64 v[208:211], v148 offset0:72 offset1:76
	ds_read2_b64 v[212:215], v152 offset0:8 offset1:12
	ds_read2_b64 v[216:219], v148 offset0:80 offset1:84
	ds_read2_b64 v[220:223], v204 offset0:96 offset1:100
	ds_read2_b64 v[224:227], v148 offset0:88 offset1:92
	v_add_u32_e32 v205, s67, v117
	ds_read2_b64 v[228:231], v156 offset0:40 offset1:44
	ds_read2_b64 v[232:235], v204 offset0:104 offset1:108
	ds_read2_b64 v[236:239], v152 offset0:16 offset1:20
	ds_read2_b64 v[240:243], v156 offset0:48 offset1:52
	s_nop 0
	s_nop 0
	s_nop 0
	s_nop 0
	s_waitcnt lgkmcnt(10)
	v_mfma_f32_16x16x32_bf16 v[68:71], v[192:195], v[196:199], 0
	ds_read2_b64 v[244:247], v204 offset0:112 offset1:116
	s_nop 0
	s_nop 0
	s_nop 0
	s_waitcnt lgkmcnt(10)
	v_mfma_f32_16x16x32_bf16 v[72:75], v[192:195], v[200:203], 0
	ds_read2_b64 v[192:195], v152 offset0:24 offset1:28
	s_nop 0
	s_nop 0
	s_nop 0
	s_waitcnt lgkmcnt(7)
	v_mfma_f32_16x16x32_bf16 v[76:79], v[220:223], v[196:199], 0
	s_cmp_eq_u32 s64, 0
	v_mfma_f32_16x16x32_bf16 v[84:87], v[220:223], v[200:203], 0
	ds_read2_b64 v[220:223], v156 offset0:56 offset1:60
	s_nop 0
	v_mfma_f32_16x16x32_bf16 v[68:71], v[208:211], v[212:215], v[68:71]
	s_waitcnt lgkmcnt(6)
	v_mfma_f32_16x16x32_bf16 v[80:83], v[208:211], v[228:231], v[72:75]
	ds_read2_b64 v[208:211], v204 offset0:120 offset1:124
	s_nop 2
	s_nop 0
	s_waitcnt lgkmcnt(6)
	v_mfma_f32_16x16x32_bf16 v[76:79], v[232:235], v[212:215], v[76:79]
	v_mfma_f32_16x16x32_bf16 v[84:87], v[232:235], v[228:231], v[84:87]
	ds_read_b128 v[232:235], v205 offset:37888
	s_nop 0
	s_waitcnt lgkmcnt(6)
	v_mfma_f32_16x16x32_bf16 v[92:95], v[216:219], v[236:239], v[68:71]
	s_nop 2
	s_nop 0
	s_waitcnt lgkmcnt(5)
	v_mfma_f32_16x16x32_bf16 v[88:91], v[216:219], v[240:243], v[80:83]
	v_add_u32_e32 v204, s67, v124
	s_nop 2
	s_nop 0
	s_waitcnt lgkmcnt(4)
	v_mfma_f32_16x16x32_bf16 v[96:99], v[244:247], v[236:239], v[76:79]
	s_nop 2
	s_nop 0
	v_mfma_f32_16x16x32_bf16 v[84:87], v[244:247], v[240:243], v[84:87]
	ds_read_b128 v[216:219], v204 offset:37888
	s_nop 0
	s_waitcnt lgkmcnt(4)
	v_mfma_f32_16x16x32_bf16 v[152:155], v[224:227], v[192:195], v[92:95]
	s_waitcnt lgkmcnt(3)
	v_mfma_f32_16x16x32_bf16 v[92:95], v[224:227], v[220:223], v[88:91]
	ds_read_b128 v[224:227], v205 offset:38016
	s_nop 0
	ds_read_b128 v[244:247], v205 offset:38080
	s_nop 4
	v_cndmask_b32_e64 v164, 0, v153, s[10:11]
	v_cndmask_b32_e64 v165, v154, 0, s[16:17]
	s_waitcnt lgkmcnt(4)
	v_mfma_f32_16x16x32_bf16 v[88:91], v[208:211], v[192:195], v[96:99]
	s_nop 2
	v_mov_b32_e32 v96, s51
	v_cndmask_b32_e64 v96, v152, v96, s[8:9]
	v_cndmask_b32_e64 v163, v96, v152, s[10:11]
	v_mov_b32_e32 v96, s51
	v_cndmask_b32_e64 v96, v92, v96, s[12:13]
	v_mfma_f32_16x16x32_bf16 v[84:87], v[208:211], v[220:223], v[84:87]
	ds_read_b128 v[208:211], v205 offset:38144
	s_nop 0
	v_cndmask_b32_e64 v168, v96, v92, s[14:15]
	s_nop 0
	v_cndmask_b32_e64 v166, v155, 0, s[18:19]
	s_nop 0
	s_nop 0
	s_waitcnt lgkmcnt(4)
	v_pk_mul_f32 v[156:157], v[22:23], v[234:235]
	v_pk_mul_f32 v[158:159], v[20:21], v[232:233]
	ds_read_b128 v[232:235], v205 offset:38208
	v_cndmask_b32_e64 v169, 0, v93, s[14:15]
	s_waitcnt lgkmcnt(4)
	v_pk_mul_f32 v[160:161], v[26:27], v[218:219]
	v_pk_mul_f32 v[98:99], v[24:25], v[216:217]
	ds_read_b128 v[216:219], v205 offset:38272
	v_cvt_pk_bf16_f32 v96, v158, v159
	v_cvt_pk_bf16_f32 v97, v156, v157
	v_cvt_pk_bf16_f32 v98, v98, v99
	v_cvt_pk_bf16_f32 v99, v160, v161
	v_cndmask_b32_e64 v170, v94, 0, s[20:21]
	v_cndmask_b32_e64 v171, v95, 0, s[22:23]
	s_nop 0
	v_mfma_f32_16x16x32_bf16 v[56:59], v[96:99], v[196:199], 0
	ds_read_b128 v[196:199], v205 offset:38336
	v_add_u32_e32 v204, v162, v122
	s_waitcnt lgkmcnt(5)
	v_pk_mul_f32 v[156:157], v[30:31], v[226:227]
	v_pk_mul_f32 v[158:159], v[28:29], v[224:225]
	ds_read_b128 v[224:227], v205 offset:38400
	s_nop 0
	s_waitcnt lgkmcnt(5)
	v_pk_mul_f32 v[160:161], v[34:35], v[246:247]
	v_pk_mul_f32 v[94:95], v[32:33], v[244:245]
	v_add_u32_e32 v206, 0x6800, v204
	v_mfma_f32_16x16x32_bf16 v[52:55], v[96:99], v[200:203], 0
	ds_read2_b64 v[200:203], v206 offset0:128 offset1:132
	v_add_u32_e32 v204, v162, v133
	v_add_u32_e32 v206, 0x4800, v204
	v_add_u32_e32 v207, 0x4000, v204
	v_mov_b32_e32 v96, s51
	v_cvt_pk_bf16_f32 v92, v158, v159
	v_cvt_pk_bf16_f32 v93, v156, v157
	v_cvt_pk_bf16_f32 v94, v94, v95
	v_cvt_pk_bf16_f32 v95, v160, v161
	v_cndmask_b32_e64 v158, v88, v96, s[24:25]
	s_nop 0
	v_mfma_f32_16x16x32_bf16 v[56:59], v[92:95], v[212:215], v[56:59]
	ds_read2_b64 v[212:215], v207 offset0:128 offset1:132
	s_waitcnt lgkmcnt(6)
; #define LAS __attribute__((address_space(3)))
; __device__ __forceinline__ bf16x8 pack8(const f32x4 a, const f32x4 b) { const u32x4 v = {pk2(a[0], a[1]), pk2(a[2], a[3]), pk2(b[0], b[1]), pk2(b[2], b[3])}; return __builtin_bit_cast(bf16x8, v); }
; __device__ __forceinline__ void hgrn_chunked_bh(const Ctx& F, int b, int h) {
;     ...
;                 const bf16x8 sA = pack8(st[2 * s] * e0, st[2 * s + 1] * e1);
; #pragma unroll
;                 for (int nt = 0; nt < 2; ++nt) oT[nt] = __builtin_amdgcn_mfma_f32_16x16x32_bf16(sA, qf[s][nt], oT[nt], 0, 0, 0);
;             }
;             const bf16x8 vA = ld_frag2(Ls + H_VT + (16 * w + c16) * HTP + 8 * g);
; #pragma unroll
;             for (int nt = 0; nt < 2; ++nt) oT[nt] = __builtin_amdgcn_mfma_f32_16x16x32_bf16(vA, pack8(at[0][nt], at[1][nt]), oT[nt], 0, 0, 0);
; #pragma unroll
;             for (int mt = 0; mt < 8; ++mt) { const f32x4 el = *(const LAS f32x4*)(Ls + H_EL + (16 * mt + 4 * g) * 4);
;                 const bf16x8 kdA = ld_frag2(Ls + H_KD + (16 * mt + c16) * HTP + 8 * g);
;                 st[mt] = __builtin_amdgcn_mfma_f32_16x16x32_bf16(kdA, vA, st[mt] * el, 0, 0, 0); }
; #pragma unroll
;             for (int nt = 0; nt < 2; ++nt) *(LAS f32x4*)(Ls + H_O + (c16 + 16 * nt) * HOP + (16 * w + 4 * g) * 4) = oT[nt];
	v_pk_mul_f32 v[154:155], v[38:39], v[210:211]
	v_pk_mul_f32 v[152:153], v[36:37], v[208:209]
	ds_read_b128 v[208:211], v205 offset:38848
	s_nop 0
	s_waitcnt lgkmcnt(6)
	v_pk_mul_f32 v[156:157], v[42:43], v[234:235]
	v_pk_mul_f32 v[98:99], v[40:41], v[232:233]
	ds_read_b128 v[232:235], v205 offset:38464
	v_cvt_pk_bf16_f32 v96, v152, v153
	v_cvt_pk_bf16_f32 v97, v154, v155
	v_cvt_pk_bf16_f32 v98, v98, v99
	v_cvt_pk_bf16_f32 v99, v156, v157
	v_mfma_f32_16x16x32_bf16 v[52:55], v[92:95], v[228:231], v[52:55]
	ds_read2_b64 v[228:231], v206 offset0:32 offset1:36
	s_nop 0
	v_cndmask_b32_e64 v92, v89, 0, s[26:27]
	v_cndmask_b32_e64 v90, v90, 0, s[28:29]
	v_mfma_f32_16x16x32_bf16 v[52:55], v[96:99], v[240:243], v[52:55]
	ds_read_b128 v[240:243], v205 offset:38528
	v_mov_b32_e32 v68, s51
	v_cndmask_b32_e64 v84, v84, v68, s[8:9]
	s_nop 0
	v_mfma_f32_16x16x32_bf16 v[56:59], v[96:99], v[236:239], v[56:59]
	ds_read2_b64 v[236:239], v206 offset0:192 offset1:196
	s_waitcnt lgkmcnt(9)
	v_pk_mul_f32 v[72:73], v[46:47], v[218:219]
	v_pk_mul_f32 v[74:75], v[44:45], v[216:217]
	v_add_u32_e32 v206, 0x5800, v204
	v_add_u32_e32 v207, 0x5000, v204
	s_nop 0
	s_waitcnt lgkmcnt(8)
	v_pk_mul_f32 v[88:89], v[50:51], v[198:199]
	v_pk_mul_f32 v[62:63], v[48:49], v[196:197]
	ds_read2_b64 v[196:199], v207 offset0:96 offset1:100
	s_nop 0
	v_cvt_pk_bf16_f32 v60, v74, v75
	v_cvt_pk_bf16_f32 v61, v72, v73
	v_cvt_pk_bf16_f32 v62, v62, v63
	v_cvt_pk_bf16_f32 v63, v88, v89
	s_nop 0
	ds_read_b128 v[216:219], v205 offset:38592
	v_cndmask_b32_e64 v72, v91, 0, s[30:31]
	v_mfma_f32_16x16x32_bf16 v[56:59], v[60:63], v[192:195], v[56:59]
	ds_read2_b64 v[192:195], v206 offset1:4
	v_cndmask_b32_e64 v76, v85, 0, s[34:35]
	v_cndmask_b32_e64 v77, v86, 0, s[36:37]
	v_cndmask_b32_e64 v78, v87, 0, s[38:39]
	v_mfma_f32_16x16x32_bf16 v[52:55], v[60:63], v[220:223], v[52:55]
	v_cvt_pk_bf16_f32 v60, v163, v164
	v_cvt_pk_bf16_f32 v61, v165, v166
	v_cvt_pk_bf16_f32 v62, v158, v92
	v_cvt_pk_bf16_f32 v63, v90, v72
	s_nop 0
	s_nop 0
	s_waitcnt lgkmcnt(9)
	v_mfma_f32_16x16x32_bf16 v[56:59], v[200:203], v[60:63], v[56:59]
	s_nop 0
	s_nop 0
	v_cvt_pk_bf16_f32 v60, v168, v169
	v_cvt_pk_bf16_f32 v61, v170, v171
	v_cvt_pk_bf16_f32 v62, v84, v76
	v_cvt_pk_bf16_f32 v63, v77, v78
	s_nop 0
	s_nop 0
	v_mfma_f32_16x16x32_bf16 v[52:55], v[200:203], v[60:63], v[52:55]
	s_nop 0
	v_pk_mul_f32 v[20:21], v[20:21], v[224:225]
	v_pk_mul_f32 v[22:23], v[22:23], v[226:227]
	ds_read_b128 v[224:227], v205 offset:38656
	s_waitcnt lgkmcnt(7)
	v_pk_mul_f32 v[24:25], v[24:25], v[232:233]
	v_pk_mul_f32 v[26:27], v[26:27], v[234:235]
	ds_read2_b64 v[232:235], v206 offset0:160 offset1:164
	v_mfma_f32_16x16x32_bf16 v[20:23], v[212:215], v[200:203], v[20:23]
	ds_read_b128 v[212:215], v205 offset:38720
	s_nop 0
	s_nop 0
	s_nop 0
	v_pk_mul_f32 v[48:49], v[48:49], v[208:209]
	s_waitcnt lgkmcnt(8)
	v_mfma_f32_16x16x32_bf16 v[24:27], v[228:231], v[200:203], v[24:27]
	ds_read_b128 v[228:231], v205 offset:38784
	v_add_u32_e32 v207, 0x6000, v204
	s_nop 0
	s_waitcnt lgkmcnt(8)
	v_pk_mul_f32 v[28:29], v[28:29], v[240:241]
	v_pk_mul_f32 v[30:31], v[30:31], v[242:243]
	ds_read2_b64 v[240:243], v207 offset0:64 offset1:68
	s_nop 0
	s_nop 0
	s_waitcnt lgkmcnt(8)
	v_mfma_f32_16x16x32_bf16 v[28:31], v[236:239], v[200:203], v[28:31]
	ds_read2_b64 v[236:239], v207 offset0:224 offset1:228
	s_nop 0
	s_nop 0
	v_pk_mul_f32 v[50:51], v[50:51], v[210:211]
	s_waitcnt lgkmcnt(7)
	v_pk_mul_f32 v[32:33], v[32:33], v[216:217]
	v_pk_mul_f32 v[34:35], v[34:35], v[218:219]
	s_nop 0
	s_waitcnt lgkmcnt(5)
	v_pk_mul_f32 v[36:37], v[36:37], v[224:225]
	v_mfma_f32_16x16x32_bf16 v[32:35], v[196:199], v[200:203], v[32:35]
	s_nop 0
	v_pk_mul_f32 v[38:39], v[38:39], v[226:227]
	s_nop 1
	v_mfma_f32_16x16x32_bf16 v[36:39], v[192:195], v[200:203], v[36:39]
	s_nop 0
	s_waitcnt lgkmcnt(3)
	v_pk_mul_f32 v[40:41], v[40:41], v[212:213]
	v_pk_mul_f32 v[42:43], v[42:43], v[214:215]
	s_waitcnt lgkmcnt(2)
	v_pk_mul_f32 v[44:45], v[44:45], v[228:229]
	v_mfma_f32_16x16x32_bf16 v[40:43], v[232:235], v[200:203], v[40:43]
	s_nop 0
	s_nop 0
	v_pk_mul_f32 v[46:47], v[46:47], v[230:231]
	s_nop 0
	s_waitcnt lgkmcnt(1)
	v_mfma_f32_16x16x32_bf16 v[44:47], v[240:243], v[200:203], v[44:47]
	s_nop 0
	s_waitcnt lgkmcnt(0)
	v_mfma_f32_16x16x32_bf16 v[48:51], v[236:239], v[200:203], v[48:51]
	v_add3_u32 v60, v205, s33, v134
	ds_write_b128 v60, v[56:59] offset:40960
	ds_write_b128 v60, v[52:55] offset:49408
	s_cbranch_scc1 .LBB0_1378
	s_cmp_lt_u32 s64, 0xf80000
	s_cbranch_scc0 .Lhg_w0
	s_waitcnt vmcnt(3)
	s_branch .Lhg_wd
